# unit prologue: DMA before Q wait, async queue pop; fox flags via b128; norm bf16 unpack deferred
# baseline (speedup 1.0000x reference)
; __device__ __forceinline__ unsigned pk2(float lo, float hi) { f32x2v v = {lo, hi}; bf16x2_t b = __builtin_convertvector(v, bf16x2_t); return __builtin_bit_cast(unsigned, b); }
; __device__ __forceinline__ void norm_phase(LAS unsigned char* lds, const Args& a, int layer) {
;     ...
;         for (int r = wid; r < SEGROWS; r += 8) {
;             const int row = row0 + r, P = row % LP, grw = g_row(row / LP, P);
;             f32x4 v[4];
; #pragma unroll
;             for (int jj = 0; jj < 4; ++jj) v[jj] = nh[jj] + ny[jj];
;             if (r + 8 < SEGROWS) NORM_LOAD(r + 8);
; #pragma unroll
;             for (int jj = 0; jj < 4; ++jj) { u32x2 o; o.x = pk2(v[jj].x, v[jj].y); o.y = pk2(v[jj].z, v[jj].w); if (grw >= 0) *(u32x2*)(H + (size_t)grw * DM + 256 * jj + 4 * lane) = o; }
.LBB0_94:
	s_or_b64 exec, exec, s[4:5]
	s_waitcnt vmcnt(0)
	s_andn2_b64 vcc, s[6:7], s[12:13]
	s_cbranch_vccz .Lnorm_nounpack
	v_and_b32_e32 v224, v224, v190
	v_and_b32_e32 v225, v225, v190
	v_and_b32_e32 v226, v226, v190
	v_and_b32_e32 v227, v227, v190
	v_and_b32_e32 v228, v228, v190
	v_and_b32_e32 v229, v229, v190
	v_and_b32_e32 v230, v230, v190
	v_and_b32_e32 v231, v231, v190
	v_and_b32_e32 v232, v232, v190
	v_and_b32_e32 v233, v233, v190
	v_and_b32_e32 v234, v234, v190
	v_and_b32_e32 v235, v235, v190
	v_and_b32_e32 v236, v236, v190
	v_and_b32_e32 v237, v237, v190
	v_and_b32_e32 v238, v238, v190
	v_and_b32_e32 v239, v239, v190
	v_lshlrev_b32_e32 v18, 16, v224
	v_and_b32_e32 v19, 0xffff0000, v224
	v_lshlrev_b32_e32 v20, 16, v225
	v_and_b32_e32 v21, 0xffff0000, v225
	v_lshlrev_b32_e32 v22, 16, v228
	v_and_b32_e32 v23, 0xffff0000, v228
	v_lshlrev_b32_e32 v24, 16, v229
	v_and_b32_e32 v25, 0xffff0000, v229
	v_lshlrev_b32_e32 v26, 16, v232
	v_and_b32_e32 v27, 0xffff0000, v232
	v_lshlrev_b32_e32 v28, 16, v233
	v_and_b32_e32 v29, 0xffff0000, v233
	v_lshlrev_b32_e32 v30, 16, v236
	v_and_b32_e32 v31, 0xffff0000, v236
	v_lshlrev_b32_e32 v32, 16, v237
	v_and_b32_e32 v33, 0xffff0000, v237
	v_lshlrev_b32_e32 v123, 16, v226
	v_and_b32_e32 v120, 0xffff0000, v226
	v_lshlrev_b32_e32 v117, 16, v227
	v_and_b32_e32 v114, 0xffff0000, v227
	v_lshlrev_b32_e32 v122, 16, v230
	v_and_b32_e32 v119, 0xffff0000, v230
	v_lshlrev_b32_e32 v116, 16, v231
	v_and_b32_e32 v113, 0xffff0000, v231
	v_lshlrev_b32_e32 v121, 16, v234
	v_and_b32_e32 v118, 0xffff0000, v234
	v_lshlrev_b32_e32 v115, 16, v235
	v_and_b32_e32 v1, 0xffff0000, v235
	v_lshlrev_b32_e32 v127, 16, v238
	v_and_b32_e32 v126, 0xffff0000, v238
	v_lshlrev_b32_e32 v125, 16, v239
	v_and_b32_e32 v124, 0xffff0000, v239
.Lnorm_nounpack:
	v_mov_b64_e32 v[48:49], v[32:33]
	s_add_i32 s22, s22, 8
	v_add_u32_e32 v112, 0x100, v112
	s_and_b64 vcc, exec, s[12:13]
	v_mov_b64_e32 v[46:47], v[30:31]
	v_mov_b64_e32 v[44:45], v[28:29]
	v_mov_b64_e32 v[42:43], v[26:27]
	v_mov_b64_e32 v[40:41], v[24:25]
	v_mov_b64_e32 v[38:39], v[22:23]
	v_mov_b64_e32 v[36:37], v[20:21]
	v_mov_b64_e32 v[34:35], v[18:19]
	v_mov_b32_e32 v58, v123
	v_mov_b32_e32 v59, v120
	v_mov_b32_e32 v64, v117
	v_mov_b32_e32 v65, v114
	v_mov_b32_e32 v60, v122
	v_mov_b32_e32 v61, v119
	v_mov_b32_e32 v66, v116
	v_mov_b32_e32 v67, v113
	v_mov_b32_e32 v62, v121
	v_mov_b32_e32 v63, v118
	v_mov_b32_e32 v68, v115
	v_mov_b32_e32 v69, v1
	v_mov_b32_e32 v70, v127
	v_mov_b32_e32 v71, v126
	v_mov_b32_e32 v72, v125
	v_mov_b32_e32 v73, v124
	s_cbranch_vccnz .LBB0_65

.LBB0_105:
	s_cmp_lt_i32 s5, 0
	s_cselect_b64 s[14:15], -1, 0
	v_cndmask_b32_e64 v190, -1, 0, s[14:15]
	s_max_i32 s18, s5, 0
	s_mov_b32 s19, s17
	s_lshl_b64 s[18:19], s[18:19], 11
	v_lshl_add_u64 v[2:3], v[52:53], 0, s[18:19]
	v_lshl_add_u64 v[6:7], v[54:55], 0, s[18:19]
	global_load_dwordx2 v[224:225], v[2:3], off
	global_load_dwordx2 v[226:227], v[6:7], off
	global_load_dwordx2 v[228:229], v[2:3], off offset:512
	global_load_dwordx2 v[230:231], v[6:7], off offset:512
	global_load_dwordx2 v[232:233], v[2:3], off offset:1024
	global_load_dwordx2 v[234:235], v[6:7], off offset:1024
	global_load_dwordx2 v[236:237], v[2:3], off offset:1536
	global_load_dwordx2 v[238:239], v[6:7], off offset:1536
	s_branch .LBB0_115

; __device__ __forceinline__ void attn_phase(LAS unsigned char* lds, const Args& a, int layer, unsigned* counters) {
;     ...
;     for (;;) {
;         __syncthreads();
;         if (tid == 0) {
;             int got = -1, q = qx, tr = tried, i = ip;
;             for (;;) { if (i < 260) { got = q * 260 + i; break; } q = (q + 1) & 7; ++tr; if (tr >= 8) break; i = (int)atomicAdd(counters + 64 * q, 1u); }
;             uw[0] = got; uw[1] = q; uw[2] = tr;
.LBB0_476:
.LBB0_477:
	s_barrier
	s_and_saveexec_b64 s[4:5], s[52:53]
	s_cbranch_execz .LBB0_489
	s_movk_i32 s0, 0x103
	s_waitcnt vmcnt(0)
	v_cmp_lt_i32_e32 vcc, s0, v235
	s_mov_b64 s[8:9], -1
	v_mov_b32_e32 v1, s33
	v_mov_b32_e32 v3, s27
	v_mov_b32_e32 v2, v235
	s_and_saveexec_b64 s[6:7], vcc
	s_cbranch_execz .LBB0_486
	s_max_i32 s0, s33, 7
	s_add_i32 s0, s0, 1
	s_mov_b64 s[8:9], 0
	v_mov_b32_e32 v1, s33
	s_branch .LBB0_482

; __device__ __forceinline__ int rfl(int v) { return __builtin_amdgcn_readfirstlane(v); }
; __device__ __forceinline__ void attn_phase(LAS unsigned char* lds, const Args& a, int layer, unsigned* counters) {
;     ...
;         }
;         __syncthreads();
;         const int u = rfl(uw[0]); qx = rfl(uw[1]); tried = rfl(uw[2]);
;         if (u < 0) break;
;         if (tid == 0) ip = (int)atomicAdd(counters + 64 * qx, 1u);
.LBB0_489:
	s_or_b64 exec, exec, s[4:5]
	v_mov_b32_e32 v1, s49
	s_waitcnt lgkmcnt(0)
	s_barrier
	ds_read_b32 v1, v1
	s_waitcnt lgkmcnt(0)
	v_readfirstlane_b32 s0, v1
	v_mov_b32_e32 v1, s50
	ds_read_b32 v1, v1
	s_cmp_lt_i32 s0, 0
	s_waitcnt lgkmcnt(0)
	v_readfirstlane_b32 s27, v1
	v_mov_b32_e32 v1, s51
	ds_read_b32 v1, v1
	s_waitcnt lgkmcnt(0)
	v_readfirstlane_b32 s33, v1
	s_cbranch_scc1 .LBB0_532
	s_and_saveexec_b64 s[4:5], s[52:53]
	s_cbranch_execz .LBB0_494
	s_mov_b64 s[8:9], exec
	v_mbcnt_lo_u32_b32 v1, s8, 0
	v_mbcnt_hi_u32_b32 v1, s9, v1
	v_cmp_eq_u32_e32 vcc, 0, v1
	s_and_saveexec_b64 s[6:7], vcc
	s_cbranch_execz .LBB0_493
	s_lshl_b32 s2, s27, 6
	s_ashr_i32 s3, s2, 31
	s_lshl_b64 s[2:3], s[2:3], 2
	s_add_u32 s2, s40, s2
	s_addc_u32 s3, s41, s3
	s_bcnt1_i32_b64 s1, s[8:9]
	v_mov_b32_e32 v2, s1
	global_atomic_add v235, v0, v2, s[2:3] offset:256 sc0

; template <bool FOX> ...
;     const int tid = opaque_tid(), lane = tid & 63, wid = rfl(tid >> 6), stream = wid >> 2, wq = wid & 3, l31 = lane & 31, hi = lane >> 5;
;     constexpr int NCB = FOX ? 2 : 4;
;     const size_t rowb = (size_t)b * LP;
;     const int q0 = j * 128, qloc128 = 32 * wq + l31, qrow = q0 + qloc128;
;     const int tq = 2 * j + (wq >> 1);
;     const int NT = 2 * j + 1;
;     bf16x8 qf[4];
;     { const bf16_t* qp = QALL + (rowb + qrow) * DM + (FOX ? 512 : 0) + 128 * g + 64 * stream + 8 * hi;
; #pragma unroll
;       for (int s = 0; s < 4; ++s) qf[s] = *(const bf16x8*)(qp + 16 * s); }
;     float cq2 = 0.f;
;     if (FOX) cq2 = CF[(rowb + qrow) * 8 + 2 * g + stream] * LOG2E;
;     const int r4 = lane >> 4, c16 = lane & 15;
;     const int chA = c16 ^ ((r4 << 2) | ((2 * wid) & 3)), chB = c16 ^ ((r4 << 2) | ((2 * wid + 1) & 3));
;     const bf16_t* kgA = K + (rowb + 8 * wid + r4) * 512 + 128 * g + 8 * chA;
;     const bf16_t* kgB = K + (rowb + 8 * wid + 4 + r4) * 512 + 128 * g + 8 * chB;
;     const bf16_t* vgA = V + (rowb + 8 * wid + r4) * 512 + 128 * g + 8 * chA;
;     const bf16_t* vgB = V + (rowb + 8 * wid + 4 + r4) * 512 + 128 * g + 8 * chB;
;     const float* cfg = CF + (rowb + lane) * 8 + 2 * g + (wid & 1);
;     ...
;     const unsigned krow = (l31 & ~12u) | ((l31 & 4u) << 1) | ((l31 & 8u) >> 1);
;     unsigned koff[4];
; #pragma unroll
;     for (int s = 0; s < 4; ++s) koff[s] = offb(krow, 8 * stream + 2 * s + hi);
;     unsigned voff[NCB][2];
; #pragma unroll
;     for (int cb = 0; cb < NCB; ++cb)
; #pragma unroll
;         for (int t = 0; t < 2; ++t) voff[cb][t] = 16384u + tr_addr(lane, FOX ? 2 * stream + cb : cb, 0, t);
;     f32x16 o[NCB];
; #pragma unroll
; __device__ __forceinline__ void attn_phase(LAS unsigned char* lds, const Args& a, int layer, unsigned* counters) {
;     ...
;         const int q = u / 260, i = u % 260;
;         if (i < 130) { const int j = NBLK - 1 - (i >> 1), bh = q + 8 * (i & 1); attn_unit<false>(lds, bh >> 2, bh & 3, j, QALL, KD, VD, GD, CF, a.subln + layer * 128, lam, oml, 1.42f * kinfd4[bh & 3], AO); }
;         else { const int v = i - 130; const int j = NBLK - 1 - (v >> 1), bh = q + 8 * (v & 1); const int g = bh & 3; const float kinf = fmaxf(kinf8[2 * g], kinf8[2 * g + 1]);
;                attn_unit<true>(lds, bh >> 2, g, j, QALL, KF, VF, GF, CF, nullptr, 0.f, 0.f, kinf, AO); }
.LBB0_494:
	s_or_b64 exec, exec, s[4:5]
	s_mul_hi_u32 s1, s0, 0xfc0fc0fd
	s_lshr_b32 s6, s1, 8
	s_mul_i32 s2, s6, 0x104
	s_sub_i32 s35, s0, s2
	s_bfe_u32 s34, s1, 0x20008
	s_cmpk_gt_u32 s35, 0x81
	s_mov_b64 s[2:3], -1
	s_cbranch_scc0 .LBB0_538
	s_add_i32 s0, s35, 0xffffff7e
	s_lshr_b32 s2, s0, 1
	s_lshl_b32 s0, s35, 3
	s_and_b32 s0, s0, 8
	v_mov_b32_e32 v3, v210
	s_add_i32 s0, s0, s6
	v_writelane_b32 v250, s6, 3
	v_readfirstlane_b32 s1, v3
	s_lshr_b32 s6, s0, 2
	s_ashr_i32 s0, s1, 6
	s_sub_i32 s3, 64, s2
	s_ashr_i32 s4, s1, 8
	s_and_b32 s1, s0, 3
	s_lshl_b32 s8, s3, 7
	s_lshl_b32 s5, s1, 5
	v_and_b32_e32 v2, 31, v3
	s_or_b32 s5, s5, s8
	v_or_b32_e32 v134, s5, v2
	v_mov_b32_e32 v135, v0
	s_mul_hi_u32 s9, s6, 0x2080
	s_mul_i32 s10, s6, 0x2080
	v_writelane_b32 v250, s6, 4
	v_mad_u64_u32 v[136:137], s[6:7], s6, v222, v[134:135]
	v_readlane_b32 s6, v253, 30
	v_lshlrev_b64 v[4:5], 11, v[136:137]
	v_readlane_b32 s7, v253, 31
	s_lshl_b32 s16, s34, 8
	s_lshl_b32 s14, s4, 6
	v_lshl_add_u64 v[4:5], s[6:7], 0, v[4:5]
	v_bfe_u32 v17, v3, 5, 1
	v_lshl_add_u64 v[4:5], v[4:5], 0, s[16:17]
	s_ashr_i32 s15, s14, 31
	v_lshl_add_u64 v[4:5], s[14:15], 1, v[4:5]
	v_lshlrev_b32_e32 v6, 4, v17
	v_mov_b32_e32 v7, v0
	v_lshl_add_u64 v[4:5], v[4:5], 0, v[6:7]
	global_load_dwordx4 v[82:85], v[4:5], off offset:1024
	global_load_dwordx4 v[86:89], v[4:5], off offset:1056
	global_load_dwordx4 v[90:93], v[4:5], off offset:1088
	global_load_dwordx4 v[94:97], v[4:5], off offset:1120
	v_lshlrev_b64 v[4:5], 5, v[136:137]
	v_lshl_add_u64 v[4:5], s[46:47], 0, v[4:5]
	s_lshl_b32 s6, s34, 3
	s_mov_b32 s7, s17
	s_ashr_i32 s5, s4, 31
	v_lshl_add_u64 v[4:5], v[4:5], 0, s[6:7]
	v_lshl_add_u64 v[4:5], s[4:5], 2, v[4:5]
	global_load_dword v4, v[4:5], off
	v_bfe_u32 v5, v3, 4, 2
	s_lshl_b32 s5, s0, 1
	v_and_b32_e32 v6, 15, v3
	v_lshlrev_b32_e32 v7, 2, v5
	s_and_b32 s5, s5, 2
	v_or_b32_e32 v8, s5, v7
	v_bitop3_b32 v18, s5, v6, v7 bitop3:0x36
	s_lshl_b32 s5, s0, 3
	s_lshl_b32 s3, s3, 1
	s_ashr_i32 s11, s5, 31
	s_add_u32 s5, s10, s5
	s_addc_u32 s11, s9, s11
	v_bitop3_b32 v20, v8, v6, 1 bitop3:0x36
	v_or_b32_e32 v6, s5, v5
	v_mov_b32_e32 v7, s11
	v_lshlrev_b64 v[6:7], 10, v[6:7]
	v_readlane_b32 s12, v253, 14
	v_readlane_b32 s13, v253, 15
	v_or_b32_e32 v10, 0x1000, v6
	v_mov_b32_e32 v11, v7
	v_and_b32_e32 v1, 63, v3
	v_lshl_add_u64 v[8:9], s[12:13], 0, v[6:7]
	v_lshl_add_u64 v[12:13], s[12:13], 0, v[10:11]
	v_readlane_b32 s12, v253, 16
	v_readlane_b32 s13, v253, 17
	v_or_b32_e32 v14, s10, v1
	v_mov_b32_e32 v15, s9
	v_lshl_add_u64 v[6:7], s[12:13], 0, v[6:7]
	v_lshlrev_b64 v[14:15], 5, v[14:15]
	v_lshl_add_u64 v[6:7], v[6:7], 0, s[16:17]
	v_lshl_add_u64 v[10:11], s[12:13], 0, v[10:11]
	v_lshl_add_u64 v[14:15], s[46:47], 0, v[14:15]
	s_and_b32 s5, s0, 1
	v_lshlrev_b32_e32 v18, 4, v18
	v_mov_b32_e32 v19, v0
	v_lshl_add_u64 v[10:11], v[10:11], 0, s[16:17]
	s_or_b32 s9, s3, 1
	v_lshl_add_u64 v[8:9], v[8:9], 0, s[16:17]
	v_lshl_add_u64 v[12:13], v[12:13], 0, s[16:17]
	v_lshl_add_u64 v[138:139], v[6:7], 0, v[18:19]
	v_lshl_add_u64 v[6:7], v[14:15], 0, s[6:7]
	s_lshl_b32 s16, s5, 2
	s_lshl_b32 s6, s0, 11
	v_lshl_add_u64 v[140:141], v[8:9], 0, v[18:19]
	v_lshlrev_b32_e32 v8, 4, v20
	v_mov_b32_e32 v9, v0
	v_lshl_add_u64 v[146:147], v[6:7], 0, s[16:17]
	s_add_i32 s30, s6, 0
	s_lshl_b32 s16, s9, 16
	v_lshl_add_u64 v[144:145], v[12:13], 0, v[8:9]
	v_lshl_add_u64 v[6:7], v[140:141], 0, s[16:17]
	s_mov_b32 m0, s30
	s_lshl_b32 s5, s5, 8
	global_load_lds_dwordx4 v[6:7], off
	v_lshl_add_u64 v[6:7], v[144:145], 0, s[16:17]
	s_add_i32 m0, s30, 0x400
	v_lshl_add_u64 v[142:143], v[10:11], 0, v[8:9]
	global_load_lds_dwordx4 v[6:7], off
	v_lshl_add_u64 v[6:7], v[138:139], 0, s[16:17]
	s_add_i32 m0, s30, 0x4000
	s_add_i32 s5, s5, 0
	global_load_lds_dwordx4 v[6:7], off
	v_lshl_add_u64 v[6:7], v[142:143], 0, s[16:17]
	s_add_i32 m0, s30, 0x4400
	s_lshl_b32 s16, s9, 11
	s_add_i32 s31, s5, 0x20000
	global_load_lds_dwordx4 v[6:7], off
	v_lshl_add_u64 v[6:7], v[146:147], 0, s[16:17]
	s_mov_b32 m0, s31
	s_nop 0
	global_load_lds_dword v[6:7], off
	s_waitcnt vmcnt(5)
	v_lshlrev_b32_e32 v5, 16, v82
	v_and_b32_e32 v6, 0xffff0000, v82
	v_add_f32_e64 v5, |v5|, |v6|
	v_lshlrev_b32_e32 v6, 16, v83
	v_add_f32_e64 v5, |v6|, v5
	v_and_b32_e32 v6, 0xffff0000, v83
	v_add_f32_e64 v5, |v6|, v5
	v_lshlrev_b32_e32 v6, 16, v84
	v_add_f32_e64 v5, |v6|, v5
	v_and_b32_e32 v6, 0xffff0000, v84
	v_add_f32_e64 v5, |v6|, v5
	v_lshlrev_b32_e32 v6, 16, v85
	v_add_f32_e64 v5, |v6|, v5
	v_and_b32_e32 v6, 0xffff0000, v85
	v_add_f32_e64 v5, |v6|, v5
	v_lshlrev_b32_e32 v6, 16, v86
	v_add_f32_e64 v5, |v6|, v5
	v_and_b32_e32 v6, 0xffff0000, v86
	v_add_f32_e64 v5, |v6|, v5
	v_lshlrev_b32_e32 v6, 16, v87
	v_add_f32_e64 v5, |v6|, v5
	v_and_b32_e32 v6, 0xffff0000, v87
	v_add_f32_e64 v5, |v6|, v5
	v_lshlrev_b32_e32 v6, 16, v88
	v_add_f32_e64 v5, |v6|, v5
	v_and_b32_e32 v6, 0xffff0000, v88
	v_add_f32_e64 v5, |v6|, v5
	v_lshlrev_b32_e32 v6, 16, v89
	v_add_f32_e64 v5, |v6|, v5
	v_and_b32_e32 v6, 0xffff0000, v89
	v_add_f32_e64 v5, |v6|, v5
	v_lshlrev_b32_e32 v6, 16, v90
	v_add_f32_e64 v5, |v6|, v5
	v_and_b32_e32 v6, 0xffff0000, v90
	v_add_f32_e64 v5, |v6|, v5
	v_lshlrev_b32_e32 v6, 16, v91
	v_add_f32_e64 v5, |v6|, v5
	v_and_b32_e32 v6, 0xffff0000, v91
	v_add_f32_e64 v5, |v6|, v5
	v_lshlrev_b32_e32 v6, 16, v92
	v_add_f32_e64 v5, |v6|, v5
	v_and_b32_e32 v6, 0xffff0000, v92
	v_add_f32_e64 v5, |v6|, v5
	v_lshlrev_b32_e32 v6, 16, v93
	v_add_f32_e64 v5, |v6|, v5
	v_and_b32_e32 v6, 0xffff0000, v93
	v_add_f32_e64 v5, |v6|, v5
	v_lshlrev_b32_e32 v6, 16, v94
	v_add_f32_e64 v5, |v6|, v5
	v_and_b32_e32 v6, 0xffff0000, v94
	v_add_f32_e64 v5, |v6|, v5
	v_lshlrev_b32_e32 v6, 16, v95
	v_add_f32_e64 v5, |v6|, v5
	v_and_b32_e32 v6, 0xffff0000, v95
	v_add_f32_e64 v5, |v6|, v5
	v_lshlrev_b32_e32 v6, 16, v96
	v_add_f32_e64 v5, |v6|, v5
	v_and_b32_e32 v6, 0xffff0000, v96
	v_add_f32_e64 v5, |v6|, v5
	v_lshlrev_b32_e32 v6, 16, v97
	v_add_f32_e64 v5, |v6|, v5
	v_and_b32_e32 v6, 0xffff0000, v97
	v_add_f32_e64 v5, |v6|, v5
	v_mov_b32_e32 v6, v5
	s_nop 1
	v_permlane32_swap_b32_e32 v5, v6
	s_cmp_eq_u32 s2, 64
	s_mov_b64 s[6:7], -1
	s_cbranch_scc1 .LBB0_497
	s_lshl_b32 s16, s8, 10
	s_add_i32 m0, s30, 0x8000
	v_lshl_add_u64 v[8:9], v[140:141], 0, s[16:17]
	global_load_lds_dwordx4 v[8:9], off
	v_lshl_add_u64 v[8:9], v[144:145], 0, s[16:17]
	s_add_i32 m0, s30, 0x8400
	s_mov_b64 s[6:7], 0
	global_load_lds_dwordx4 v[8:9], off
	v_lshl_add_u64 v[8:9], v[138:139], 0, s[16:17]
	s_add_i32 m0, s30, 0xc000
	s_nop 0
	global_load_lds_dwordx4 v[8:9], off
	v_lshl_add_u64 v[8:9], v[142:143], 0, s[16:17]
	s_add_i32 m0, s30, 0xc400
	s_lshl_b32 s16, s8, 5
	global_load_lds_dwordx4 v[8:9], off
	v_lshl_add_u64 v[8:9], v[146:147], 0, s[16:17]
	s_add_i32 m0, s5, 0x20200
	s_nop 0
	global_load_lds_dword v[8:9], off
	s_waitcnt vmcnt(5) lgkmcnt(0)
	s_barrier

; __device__ __forceinline__ int rfl(int v) { return __builtin_amdgcn_readfirstlane(v); }
; template <bool FOX> ...
;     ...
;         if (FOX && cont) { int any_ = 0;
; #pragma unroll
;             for (int w8 = 0; w8 < 8; ++w8) any_ |= flags[buf * 8 + w8];
;             cont = rfl(any_) != 0; }
.LBB0_524:
	s_mov_b64 s[12:13], -1
	s_cmp_lt_i32 s34, 2
	v_readfirstlane_b32 s3, v0
	v_readfirstlane_b32 s0, v0
	s_cbranch_scc1 .LBB0_526
	s_lshl_b32 s12, s18, 5
	s_add_i32 s12, s12, 0
	s_add_i32 s12, s12, 0x20840
	v_mov_b32_e32 v1, s12
	ds_read_b128 v[4:7], v1
	ds_read_b128 v[8:11], v1 offset:16
	s_add_i32 s3, s18, 1
	s_sub_i32 s0, s16, 64
	s_and_b32 s3, s3, 3
	v_add_u32_e32 v162, 1, v162
	s_waitcnt lgkmcnt(0)
	v_or3_b32 v4, v4, v5, v6
	v_or3_b32 v8, v8, v9, v10
	v_or3_b32 v4, v4, v7, v8
	v_or_b32_e32 v1, v4, v11
	s_nop 0
	v_readfirstlane_b32 s12, v1
	s_cmp_eq_u32 s12, 0
	s_cselect_b64 s[12:13], -1, 0

; template <bool FOX> ...
;     const int tid = opaque_tid(), lane = tid & 63, wid = rfl(tid >> 6), stream = wid >> 2, wq = wid & 3, l31 = lane & 31, hi = lane >> 5;
;     constexpr int NCB = FOX ? 2 : 4;
;     const size_t rowb = (size_t)b * LP;
;     const int q0 = j * 128, qloc128 = 32 * wq + l31, qrow = q0 + qloc128;
;     const int tq = 2 * j + (wq >> 1);
;     const int NT = 2 * j + 1;
;     bf16x8 qf[4];
;     { const bf16_t* qp = QALL + (rowb + qrow) * DM + (FOX ? 512 : 0) + 128 * g + 64 * stream + 8 * hi;
; #pragma unroll
;       for (int s = 0; s < 4; ++s) qf[s] = *(const bf16x8*)(qp + 16 * s); }
;     float cq2 = 0.f;
;     if (FOX) cq2 = CF[(rowb + qrow) * 8 + 2 * g + stream] * LOG2E;
;     const int r4 = lane >> 4, c16 = lane & 15;
;     const int chA = c16 ^ ((r4 << 2) | ((2 * wid) & 3)), chB = c16 ^ ((r4 << 2) | ((2 * wid + 1) & 3));
;     const bf16_t* kgA = K + (rowb + 8 * wid + r4) * 512 + 128 * g + 8 * chA;
;     const bf16_t* kgB = K + (rowb + 8 * wid + 4 + r4) * 512 + 128 * g + 8 * chB;
;     const bf16_t* vgA = V + (rowb + 8 * wid + r4) * 512 + 128 * g + 8 * chA;
;     const bf16_t* vgB = V + (rowb + 8 * wid + 4 + r4) * 512 + 128 * g + 8 * chB;
;     const float* cfg = CF + (rowb + lane) * 8 + 2 * g + (wid & 1);
;     ...
;     const unsigned krow = (l31 & ~12u) | ((l31 & 4u) << 1) | ((l31 & 8u) >> 1);
;     unsigned koff[4];
; #pragma unroll
;     for (int s = 0; s < 4; ++s) koff[s] = offb(krow, 8 * stream + 2 * s + hi);
;     unsigned voff[NCB][2];
; #pragma unroll
;     for (int cb = 0; cb < NCB; ++cb)
; #pragma unroll
;         for (int t = 0; t < 2; ++t) voff[cb][t] = 16384u + tr_addr(lane, FOX ? 2 * stream + cb : cb, 0, t);
;     f32x16 o[NCB];
; #pragma unroll
;     for (int cb = 0; cb < NCB; ++cb)
; #pragma unroll
;         for (int r = 0; r < 16; ++r) o[cb][r] = 0.f;
;     float lsum = 0.f;
;     const int qloc64 = 32 * (wq & 1) + l31;
;     constexpr float THR = 96.0f, SKIP_T = 40.0f;
;     float ub = 0.f, qb;
;     {
;         float q1 = 0.f;
; #pragma unroll
; __device__ __forceinline__ void attn_phase(LAS unsigned char* lds, const Args& a, int layer, unsigned* counters) {
;     ...
;         const int q = u / 260, i = u % 260;
;         if (i < 130) { const int j = NBLK - 1 - (i >> 1), bh = q + 8 * (i & 1); attn_unit<false>(lds, bh >> 2, bh & 3, j, QALL, KD, VD, GD, CF, a.subln + layer * 128, lam, oml, 1.42f * kinfd4[bh & 3], AO); }
.LBB0_538:
	s_and_b64 vcc, exec, s[2:3]
	s_cbranch_vccz .LBB0_476
	s_cmpk_gt_u32 s35, 0x40
	s_cselect_b32 s1, 8, 0
	s_cselect_b32 s22, 0x41, 0
	s_add_i32 s1, s1, s6
	v_mov_b32_e32 v17, v210
	s_lshr_b32 s20, s1, 2
	s_sub_i32 s22, s35, s22
	v_readfirstlane_b32 s1, v17
	s_ashr_i32 s21, s1, 6
	s_sub_i32 s0, 64, s22
	s_and_b32 s3, s21, 3
	s_lshl_b32 s4, s0, 7
	s_lshl_b32 s5, s3, 5
	s_or_b32 s4, s5, s4
	v_and_or_b32 v192, v17, 31, s4
	v_mov_b32_e32 v193, v0
	v_mad_u64_u32 v[194:195], s[4:5], s20, v222, v[192:193]
	v_readlane_b32 s4, v253, 30
	s_ashr_i32 s2, s1, 8
	v_lshlrev_b64 v[2:3], 11, v[194:195]
	v_readlane_b32 s5, v253, 31
	s_lshl_b32 s16, s34, 8
	v_bfe_u32 v1, v17, 5, 1
	v_lshl_add_u64 v[2:3], s[4:5], 0, v[2:3]
	s_lshl_b32 s4, s2, 6
	v_lshl_add_u64 v[2:3], v[2:3], 0, s[16:17]
	s_ashr_i32 s5, s4, 31
	v_lshl_add_u64 v[2:3], s[4:5], 1, v[2:3]
	v_lshlrev_b32_e32 v14, 4, v1
	v_mov_b32_e32 v15, v0
	v_lshl_add_u64 v[18:19], v[2:3], 0, v[14:15]
	global_load_dwordx4 v[2:5], v[18:19], off
	global_load_dwordx4 v[6:9], v[18:19], off offset:32
	global_load_dwordx4 v[10:13], v[18:19], off offset:64
	global_load_dwordx4 v[144:147], v[18:19], off offset:96
	v_bfe_u32 v15, v17, 4, 2
	s_lshl_b32 s4, s21, 1
	v_and_b32_e32 v18, 15, v17
	v_lshlrev_b32_e32 v19, 2, v15
	s_and_b32 s4, s4, 2
	v_or_b32_e32 v20, s4, v19
	v_bitop3_b32 v28, s4, v18, v19 bitop3:0x36
	s_lshl_b32 s4, s21, 3
	s_mul_i32 s6, s20, 0x2080
	s_ashr_i32 s5, s4, 31
	s_mul_hi_u32 s1, s20, 0x2080
	s_add_u32 s4, s6, s4
	s_addc_u32 s1, s1, s5
	v_bitop3_b32 v30, v20, v18, 1 bitop3:0x36
	v_or_b32_e32 v18, s4, v15
	v_mov_b32_e32 v19, s1
	v_readlane_b32 s4, v253, 10
	v_lshlrev_b64 v[18:19], 10, v[18:19]
	v_readlane_b32 s5, v253, 11
	v_lshl_add_u64 v[20:21], s[70:71], 0, v[18:19]
	v_or_b32_e32 v22, 0x1000, v18
	v_mov_b32_e32 v23, v19
	v_lshl_add_u64 v[18:19], s[4:5], 0, v[18:19]
	v_lshl_add_u64 v[24:25], s[70:71], 0, v[22:23]
	v_lshl_add_u64 v[26:27], v[18:19], 0, s[16:17]
	v_lshl_add_u64 v[18:19], s[4:5], 0, v[22:23]
	v_lshl_add_u64 v[22:23], v[20:21], 0, s[16:17]
	v_lshlrev_b32_e32 v28, 4, v28
	v_mov_b32_e32 v29, v0
	s_lshl_b32 s1, s21, 11
	v_lshl_add_u64 v[18:19], v[18:19], 0, s[16:17]
	v_lshl_add_u64 v[24:25], v[24:25], 0, s[16:17]
	v_lshlrev_b32_e32 v20, 4, v30
	v_mov_b32_e32 v21, v0
	v_lshl_add_u64 v[200:201], v[22:23], 0, v[28:29]
	s_add_i32 s24, s1, 0
	s_mov_b64 s[4:5], 0x10000
	v_lshl_add_u64 v[198:199], v[24:25], 0, v[20:21]
	v_lshl_add_u64 v[202:203], v[18:19], 0, v[20:21]
	v_lshl_add_u64 v[18:19], v[200:201], 0, s[4:5]
	s_mov_b32 m0, s24
	v_lshl_add_u64 v[196:197], v[26:27], 0, v[28:29]
	global_load_lds_dwordx4 v[18:19], off
	s_add_i32 m0, s24, 0x400
	v_lshl_add_u64 v[18:19], v[198:199], 0, s[4:5]
	global_load_lds_dwordx4 v[18:19], off
	s_add_i32 m0, s24, 0x4000
	v_lshl_add_u64 v[18:19], v[196:197], 0, s[4:5]
	global_load_lds_dwordx4 v[18:19], off
	s_add_i32 m0, s24, 0x4400
	v_lshl_add_u64 v[18:19], v[202:203], 0, s[4:5]
	global_load_lds_dwordx4 v[18:19], off
	s_waitcnt vmcnt(4)
	v_lshlrev_b32_e32 v15, 16, v2
	v_and_b32_e32 v22, 0xffff0000, v2
	v_add_f32_e64 v15, |v15|, |v22|
	v_lshlrev_b32_e32 v22, 16, v3
	v_add_f32_e64 v15, |v22|, v15
	v_and_b32_e32 v22, 0xffff0000, v3
	v_add_f32_e64 v15, |v22|, v15
	v_lshlrev_b32_e32 v22, 16, v4
	v_add_f32_e64 v15, |v22|, v15
	v_and_b32_e32 v22, 0xffff0000, v4
	v_add_f32_e64 v15, |v22|, v15
	v_lshlrev_b32_e32 v22, 16, v5
	v_add_f32_e64 v15, |v22|, v15
	v_and_b32_e32 v22, 0xffff0000, v5
	v_add_f32_e64 v15, |v22|, v15
	v_lshlrev_b32_e32 v22, 16, v6
	v_add_f32_e64 v15, |v22|, v15
	v_and_b32_e32 v22, 0xffff0000, v6
	v_add_f32_e64 v15, |v22|, v15
	v_lshlrev_b32_e32 v22, 16, v7
	v_add_f32_e64 v15, |v22|, v15
	v_and_b32_e32 v22, 0xffff0000, v7
	v_add_f32_e64 v15, |v22|, v15
	v_lshlrev_b32_e32 v22, 16, v8
	v_add_f32_e64 v15, |v22|, v15
	v_and_b32_e32 v22, 0xffff0000, v8
	v_add_f32_e64 v15, |v22|, v15
	v_lshlrev_b32_e32 v22, 16, v9
	v_add_f32_e64 v15, |v22|, v15
	v_and_b32_e32 v22, 0xffff0000, v9
	v_add_f32_e64 v15, |v22|, v15
	v_lshlrev_b32_e32 v22, 16, v10
	v_add_f32_e64 v15, |v22|, v15
	v_and_b32_e32 v22, 0xffff0000, v10
	v_add_f32_e64 v15, |v22|, v15
	v_lshlrev_b32_e32 v22, 16, v11
	v_add_f32_e64 v15, |v22|, v15
	v_and_b32_e32 v22, 0xffff0000, v11
	v_add_f32_e64 v15, |v22|, v15
	v_lshlrev_b32_e32 v22, 16, v12
	v_add_f32_e64 v15, |v22|, v15
	v_and_b32_e32 v22, 0xffff0000, v12
	v_add_f32_e64 v15, |v22|, v15
	v_lshlrev_b32_e32 v22, 16, v13
	v_add_f32_e64 v15, |v22|, v15
	v_and_b32_e32 v22, 0xffff0000, v13
	v_add_f32_e64 v15, |v22|, v15
	v_lshlrev_b32_e32 v22, 16, v144
	v_add_f32_e64 v15, |v22|, v15
	v_and_b32_e32 v22, 0xffff0000, v144
	v_add_f32_e64 v15, |v22|, v15
	v_lshlrev_b32_e32 v22, 16, v145
	v_add_f32_e64 v15, |v22|, v15
	v_and_b32_e32 v22, 0xffff0000, v145
	v_add_f32_e64 v15, |v22|, v15
	v_lshlrev_b32_e32 v22, 16, v146
	v_add_f32_e64 v15, |v22|, v15
	v_and_b32_e32 v22, 0xffff0000, v146
	v_add_f32_e64 v15, |v22|, v15
	v_lshlrev_b32_e32 v22, 16, v147
	v_add_f32_e64 v15, |v22|, v15
	v_and_b32_e32 v22, 0xffff0000, v147
	v_add_f32_e64 v38, |v22|, v15
	v_mov_b32_e32 v39, v38
	s_cmp_lg_u32 s22, 64
	s_nop 0
	v_permlane32_swap_b32_e32 v38, v39
	s_mov_b64 s[4:5], -1
	s_cselect_b64 s[12:13], -1, 0
	s_cmp_eq_u32 s22, 64
	s_cbranch_scc1 .LBB0_541
	s_mov_b64 s[4:5], 0x20000
	s_add_i32 m0, s24, 0x8000
	v_lshl_add_u64 v[18:19], v[200:201], 0, s[4:5]
	global_load_lds_dwordx4 v[18:19], off
	v_lshl_add_u64 v[18:19], v[198:199], 0, s[4:5]
	s_add_i32 m0, s24, 0x8400
	s_nop 0
	global_load_lds_dwordx4 v[18:19], off
	v_lshl_add_u64 v[18:19], v[196:197], 0, s[4:5]
	s_add_i32 m0, s24, 0xc000
	s_nop 0
	global_load_lds_dwordx4 v[18:19], off
	v_lshl_add_u64 v[18:19], v[202:203], 0, s[4:5]
	s_add_i32 m0, s24, 0xc400
	s_mov_b64 s[4:5], 0
	global_load_lds_dwordx4 v[18:19], off
	s_waitcnt vmcnt(4) lgkmcnt(0)
	s_barrier
